# gMLP gating items moved from phase 2 into phase 3 (run after a workgroup's pool-GEMM unit, 3 items on workgroups without one), item loop software-pipelined
# speedup vs baseline: 1.0647x; 1.0006x over previous
; #define LAS __attribute__((address_space(3)))
; DI unsigned pk2(float a, float b) { f32x2 f = {a, b}; bf16v2 r = __builtin_convertvector(f, bf16v2); return __builtin_bit_cast(unsigned, r); }
; DI float rstd_of(float ssq, float inv_n) { return __builtin_amdgcn_rsqf(ssq * inv_n + 1e-6f); }
; DI int lane_id() { int l = __builtin_amdgcn_mbcnt_hi(-1, __builtin_amdgcn_mbcnt_lo(-1, 0)); asm volatile("" : "+v"(l)); return l; }
; DI void phase2(CP& p, LAS unsigned char* lds, int wid) {
;     const int lane = lane_id(), tid = wid * 64 + lane, fr = lane & 15, fq = lane >> 4;
;     const float* Z = WSF(OFF_Z); bf16_t* DP = WSB(OFF_DP);
;     LAS unsigned char* wm = lds; LAS float* rsl = (LAS float*)(lds + 36864);
;     for (int it = blockIdx.x; it < 256 + 512; it += gridDim.x) {
;     ...
;             const int item = it - 256, nb = item >> 3, h = item & 7, t0 = nb * 128;
;             if (tid < 128) rsl[tid] = rstd_of(SSQ(1)[t0 + tid], 1.f / 1024.f);
;             __syncthreads();
;             { const int t = tid >> 2, sq = (tid & 3) * 32; const float* wrow = p.w_s + ((size_t)h * 128 + t) * 128 + sq;
; #pragma unroll
;               for (int e = 0; e < 4; ++e) { const f32x4 a = *(const f32x4*)(wrow + e * 8), b = *(const f32x4*)(wrow + e * 8 + 4); const int s0 = sq + e * 8;
;                   const float mk = ((s0 >> 6) <= (t >> 6)) ? 1.f : 0.f;
;                   u32x4 w; w.x = pk2(a[0] * mk * rsl[s0], a[1] * mk * rsl[s0 + 1]); w.y = pk2(a[2] * mk * rsl[s0 + 2], a[3] * mk * rsl[s0 + 3]);
;                   w.z = pk2(b[0] * mk * rsl[s0 + 4], b[1] * mk * rsl[s0 + 5]); w.w = pk2(b[2] * mk * rsl[s0 + 6], b[3] * mk * rsl[s0 + 7]);
;                   *(LAS u32x4*)(wm + t * 272 + s0 * 2) = w; } }
;             __syncthreads();
;             const int ch = h * 128 + 16 * wid + fr; const bf16_t* vt = WSB(OFF_VT) + (size_t)ch * 8192 + t0 + 8 * fq;
.Lp2_entry:
	s_load_dwordx2 s[8:9], s[4:5], 0xa8
	s_load_dwordx4 s[12:15], s[4:5], 0x28
	s_load_dwordx2 s[22:23], s[4:5], 0x38
	v_mov_b32_e32 v0, v2
	v_mov_b32_e32 v1, 0
	s_and_b32 s2, s88, 0xffffffc0
	v_add_u32_e32 v2, s2, v0
	v_and_b32_e32 v5, 15, v0
	v_lshrrev_b32_e32 v6, 4, v0
	v_and_b32_e32 v3, 0xff, v2
	v_lshlrev_b32_e32 v4, 3, v3
	v_lshlrev_b32_e32 v3, 4, v3
	v_lshlrev_b32_e32 v8, 7, v2
	v_bfe_u32 v9, v2, 1, 1
	v_lshrrev_b32_e32 v7, 8, v2
	v_cmp_le_u32_e32 vcc, v9, v7
	s_nop 1
	v_cndmask_b32_e64 v10, 0, 1.0, vcc
	v_mov_b32_e32 v11, v10
	v_and_b32_e32 v9, 3, v2
	v_lshlrev_b32_e32 v12, 7, v9
	v_add_u32_e32 v12, 0x9000, v12
	v_lshrrev_b32_e32 v7, 2, v2
	v_mul_u32_u24_e32 v13, 0x110, v7
	v_lshl_add_u32 v13, v9, 6, v13
	s_lshl_b32 s3, s33, 4
	v_add_u32_e32 v7, s3, v5
	v_lshlrev_b32_e32 v14, 14, v7
	v_lshl_add_u32 v14, v6, 4, v14
	v_lshl_add_u32 v7, v6, 2, s3
	v_lshlrev_b32_e32 v15, 2, v7
	v_lshlrev_b32_e32 v16, 2, v5
	v_lshlrev_b32_e32 v17, 11, v5
	v_lshl_add_u32 v17, v7, 1, v17
	v_lshlrev_b32_e32 v18, 12, v5
	v_lshl_add_u32 v18, v7, 1, v18
	v_mul_u32_u24_e32 v19, 0x110, v5
	v_lshl_add_u32 v19, v6, 4, v19
	v_and_b32_e32 v20, 0x7f, v2
	v_lshlrev_b32_e32 v20, 2, v20
	v_add_u32_e32 v21, 0x9000, v20
	v_mov_b32_e32 v23, 0x358637bd
	s_waitcnt lgkmcnt(0)
	s_add_u32 s24, s8, 0xf000000
	s_addc_u32 s25, s9, 0
	s_add_u32 s26, s8, 0x11000000
	s_addc_u32 s27, s9, 0
	s_add_u32 s28, s8, 0xe000000
	s_addc_u32 s29, s9, 0
	s_add_u32 s30, s8, 0xd000000
	s_addc_u32 s31, s9, 0
	s_add_u32 s36, s8, 0x12000000
	s_addc_u32 s37, s9, 0
	s_add_u32 s20, s8, 0xcd08000
	s_addc_u32 s21, s9, 0
	s_cmp_lg_u32 s98, 0
	s_cbranch_scc1 .Lp2_range
	s_mov_b32 s99, s6
	s_mov_b32 s100, s7
	s_movk_i32 s101, 0x300
	s_cmpk_eq_i32 s7, 0x100
	s_cselect_b32 s101, 0x100, s101
.Lp2_range:
	s_mov_b32 s39, s99
	s_cmp_ge_i32 s39, s101
	s_cbranch_scc1 .Lp2_done

; #define LAS __attribute__((address_space(3)))
; DI unsigned pk2(float a, float b) { f32x2 f = {a, b}; bf16v2 r = __builtin_convertvector(f, bf16v2); return __builtin_bit_cast(unsigned, r); }
; DI float rstd_of(float ssq, float inv_n) { return __builtin_amdgcn_rsqf(ssq * inv_n + 1e-6f); }
; DI void phase2(CP& p, LAS unsigned char* lds, int wid) {
;     ...
;             if (tid < 128) rsl[tid] = rstd_of(SSQ(1)[t0 + tid], 1.f / 1024.f);
;             __syncthreads();
;             { const int t = tid >> 2, sq = (tid & 3) * 32; const float* wrow = p.w_s + ((size_t)h * 128 + t) * 128 + sq;
; #pragma unroll
;               for (int e = 0; e < 4; ++e) { const f32x4 a = *(const f32x4*)(wrow + e * 8), b = *(const f32x4*)(wrow + e * 8 + 4); const int s0 = sq + e * 8;
;                   const float mk = ((s0 >> 6) <= (t >> 6)) ? 1.f : 0.f;
;                   u32x4 w; w.x = pk2(a[0] * mk * rsl[s0], a[1] * mk * rsl[s0 + 1]); w.y = pk2(a[2] * mk * rsl[s0 + 2], a[3] * mk * rsl[s0 + 3]);
;                   w.z = pk2(b[0] * mk * rsl[s0 + 4], b[1] * mk * rsl[s0 + 5]); w.w = pk2(b[2] * mk * rsl[s0 + 6], b[3] * mk * rsl[s0 + 7]);
;                   *(LAS u32x4*)(wm + t * 272 + s0 * 2) = w; } }
;             __syncthreads();
;             const int ch = h * 128 + 16 * wid + fr; const bf16_t* vt = WSB(OFF_VT) + (size_t)ch * 8192 + t0 + 8 * fq;
;             bf16x8 bfr[4];
; #pragma unroll
;             for (int ks = 0; ks < 4; ++ks) bfr[ks] = *(const bf16x8*)(vt + 32 * ks);
;             f32x4 acc[8];
; #pragma unroll
;             for (int tt = 0; tt < 8; ++tt) { acc[tt] = (f32x4){0.f, 0.f, 0.f, 0.f};
; #pragma unroll
;                 for (int ks = 0; ks < 4; ++ks) { const bf16x8 af = *(const LAS bf16x8*)(wm + (16 * tt + fr) * 272 + (32 * ks + 8 * fq) * 2);
;                     acc[tt] = __builtin_amdgcn_mfma_f32_16x16x32_bf16(bfr[ks], af, acc[tt], 0, 0, 0); } }
;             const int d0 = h * 128 + 16 * wid + 4 * fq; const f32x4 gv = *(const f32x4*)(p.g_v + d0);
; #pragma unroll
;             for (int tt = 0; tt < 8; ++tt) { const int t = 16 * tt + fr, tok = t0 + t; const float bs = p.b_s[h * 128 + t];
;                 const u32x2 uw = *(const u32x2*)(WSB(OFF_U) + (size_t)tok * 1024 + d0);
.Lp2_gmlp:
	s_add_i32 s2, s39, 0xffffff00
	s_and_b32 s3, s2, 7
	s_lshr_b32 s2, s2, 3
	s_lshl_b32 s2, s2, 7
	s_lshl_b32 s4, s2, 2
	s_add_u32 s10, s20, s4
	s_addc_u32 s11, s21, 0
	global_load_dword v22, v20, s[10:11]
	s_lshl_b32 s4, s3, 16
	s_add_u32 s10, s14, s4
	s_addc_u32 s11, s15, 0
	global_load_dwordx4 v[100:103], v8, s[10:11]
	global_load_dwordx4 v[104:107], v8, s[10:11] offset:16
	global_load_dwordx4 v[108:111], v8, s[10:11] offset:32
	global_load_dwordx4 v[112:115], v8, s[10:11] offset:48
	global_load_dwordx4 v[116:119], v8, s[10:11] offset:64
	global_load_dwordx4 v[120:123], v8, s[10:11] offset:80
	global_load_dwordx4 v[124:127], v8, s[10:11] offset:96
	global_load_dwordx4 v[128:131], v8, s[10:11] offset:112
	s_lshl_b32 s4, s3, 21
	s_lshl_b32 s5, s2, 1
	s_add_i32 s4, s4, s5
	s_add_u32 s10, s28, s4
	s_addc_u32 s11, s29, 0
	global_load_dwordx4 v[132:135], v14, s[10:11]
	global_load_dwordx4 v[136:139], v14, s[10:11] offset:64
	global_load_dwordx4 v[140:143], v14, s[10:11] offset:128
	global_load_dwordx4 v[144:147], v14, s[10:11] offset:192
	s_lshl_b32 s4, s3, 9
	s_add_u32 s10, s12, s4
	s_addc_u32 s11, s13, 0
	global_load_dwordx4 v[148:151], v15, s[10:11]
	s_add_u32 s10, s22, s4
	s_addc_u32 s11, s23, 0
	global_load_dword v176, v16, s[10:11]
	global_load_dword v178, v16, s[10:11] offset:64
	global_load_dword v180, v16, s[10:11] offset:128
	global_load_dword v182, v16, s[10:11] offset:192
	global_load_dword v184, v16, s[10:11] offset:256
	global_load_dword v186, v16, s[10:11] offset:320
	global_load_dword v188, v16, s[10:11] offset:384
	global_load_dword v190, v16, s[10:11] offset:448
	s_lshl_b32 s4, s2, 11
	s_lshl_b32 s5, s3, 8
	s_add_i32 s4, s4, s5
	s_add_u32 s10, s30, s4
	s_addc_u32 s11, s31, 0
	global_load_dwordx2 v[160:161], v17, s[10:11]
	s_add_u32 s10, s10, 0x8000
	s_addc_u32 s11, s11, 0
	global_load_dwordx2 v[162:163], v17, s[10:11]
	s_add_u32 s10, s10, 0x8000
	s_addc_u32 s11, s11, 0
	global_load_dwordx2 v[164:165], v17, s[10:11]
	s_add_u32 s10, s10, 0x8000
	s_addc_u32 s11, s11, 0
	global_load_dwordx2 v[166:167], v17, s[10:11]
	s_add_u32 s10, s10, 0x8000
	s_addc_u32 s11, s11, 0
	global_load_dwordx2 v[168:169], v17, s[10:11]
	s_add_u32 s10, s10, 0x8000
	s_addc_u32 s11, s11, 0
	global_load_dwordx2 v[170:171], v17, s[10:11]
	s_add_u32 s10, s10, 0x8000
	s_addc_u32 s11, s11, 0
	global_load_dwordx2 v[172:173], v17, s[10:11]
	s_add_u32 s10, s10, 0x8000
	s_addc_u32 s11, s11, 0
	global_load_dwordx2 v[174:175], v17, s[10:11]
	s_lshl_b32 s4, s2, 12
	s_add_i32 s4, s4, s5
	s_add_u32 s8, s36, s4
	s_addc_u32 s9, s37, 0
.Lp2_g_item:
	s_mov_b64 s[18:19], s[8:9]
	s_waitcnt vmcnt(0)
	v_fmamk_f32 v22, v22, 0x3a800000, v23
	v_rsq_f32_e32 v22, v22
	s_nop 0
	ds_write_b32 v21, v22
	s_waitcnt lgkmcnt(0)
	s_barrier
	ds_read_b128 v[24:27], v12
	ds_read_b128 v[28:31], v12 offset:16
	ds_read_b128 v[32:35], v12 offset:32
	ds_read_b128 v[36:39], v12 offset:48
	ds_read_b128 v[40:43], v12 offset:64
	ds_read_b128 v[44:47], v12 offset:80
	ds_read_b128 v[48:51], v12 offset:96
	ds_read_b128 v[52:55], v12 offset:112
	v_mov_b32_e32 v192, v132
	v_mov_b32_e32 v193, v133
	v_mov_b32_e32 v194, v134
	v_mov_b32_e32 v195, v135
	v_mov_b32_e32 v196, v136
	v_mov_b32_e32 v197, v137
	v_mov_b32_e32 v198, v138
	v_mov_b32_e32 v199, v139
	v_mov_b32_e32 v200, v140
	v_mov_b32_e32 v201, v141
	v_mov_b32_e32 v202, v142
	v_mov_b32_e32 v203, v143
	v_mov_b32_e32 v204, v144
	v_mov_b32_e32 v205, v145
	v_mov_b32_e32 v206, v146
	v_mov_b32_e32 v207, v147
	v_mov_b32_e32 v208, v148
	v_mov_b32_e32 v209, v149
	v_mov_b32_e32 v210, v150
	v_mov_b32_e32 v211, v151
	v_mov_b32_e32 v212, v160
	v_mov_b32_e32 v213, v161
	v_mov_b32_e32 v214, v162
	v_mov_b32_e32 v215, v163
	v_mov_b32_e32 v216, v164
	v_mov_b32_e32 v217, v165
	v_mov_b32_e32 v218, v166
	v_mov_b32_e32 v219, v167
	v_mov_b32_e32 v220, v168
	v_mov_b32_e32 v221, v169
	v_mov_b32_e32 v222, v170
	v_mov_b32_e32 v223, v171
	v_mov_b32_e32 v224, v172
	v_mov_b32_e32 v225, v173
	v_mov_b32_e32 v226, v174
	v_mov_b32_e32 v227, v175
	v_mov_b32_e32 v228, v176
	v_mov_b32_e32 v230, v178
	v_mov_b32_e32 v232, v180
	v_mov_b32_e32 v234, v182
	v_mov_b32_e32 v236, v184
	v_mov_b32_e32 v238, v186
	v_mov_b32_e32 v240, v188
	v_mov_b32_e32 v242, v190
	s_waitcnt lgkmcnt(7)
	v_pk_mul_f32 v[100:101], v[10:11], v[100:101]
	v_pk_mul_f32 v[102:103], v[10:11], v[102:103]
	v_pk_mul_f32 v[100:101], v[100:101], v[24:25]
	v_pk_mul_f32 v[102:103], v[102:103], v[26:27]
	s_waitcnt lgkmcnt(6)
	v_pk_mul_f32 v[104:105], v[10:11], v[104:105]
	v_pk_mul_f32 v[106:107], v[10:11], v[106:107]
	v_pk_mul_f32 v[104:105], v[104:105], v[28:29]
	v_pk_mul_f32 v[106:107], v[106:107], v[30:31]
	s_waitcnt lgkmcnt(5)
	v_pk_mul_f32 v[108:109], v[10:11], v[108:109]
	v_pk_mul_f32 v[110:111], v[10:11], v[110:111]
	v_pk_mul_f32 v[108:109], v[108:109], v[32:33]
	v_pk_mul_f32 v[110:111], v[110:111], v[34:35]
	s_waitcnt lgkmcnt(4)
	v_pk_mul_f32 v[112:113], v[10:11], v[112:113]
	v_pk_mul_f32 v[114:115], v[10:11], v[114:115]
	v_pk_mul_f32 v[112:113], v[112:113], v[36:37]
	v_pk_mul_f32 v[114:115], v[114:115], v[38:39]
	s_waitcnt lgkmcnt(3)
	v_pk_mul_f32 v[116:117], v[10:11], v[116:117]
	v_pk_mul_f32 v[118:119], v[10:11], v[118:119]
	v_pk_mul_f32 v[116:117], v[116:117], v[40:41]
	v_pk_mul_f32 v[118:119], v[118:119], v[42:43]
	s_waitcnt lgkmcnt(2)
	v_pk_mul_f32 v[120:121], v[10:11], v[120:121]
	v_pk_mul_f32 v[122:123], v[10:11], v[122:123]
	v_pk_mul_f32 v[120:121], v[120:121], v[44:45]
	v_pk_mul_f32 v[122:123], v[122:123], v[46:47]
	s_waitcnt lgkmcnt(1)
	v_pk_mul_f32 v[124:125], v[10:11], v[124:125]
	v_pk_mul_f32 v[126:127], v[10:11], v[126:127]
	v_pk_mul_f32 v[124:125], v[124:125], v[48:49]
	v_pk_mul_f32 v[126:127], v[126:127], v[50:51]
	s_waitcnt lgkmcnt(0)
	v_pk_mul_f32 v[128:129], v[10:11], v[128:129]
	v_pk_mul_f32 v[130:131], v[10:11], v[130:131]
	v_pk_mul_f32 v[128:129], v[128:129], v[52:53]
	v_pk_mul_f32 v[130:131], v[130:131], v[54:55]
	v_cvt_pk_bf16_f32 v24, v100, v101
	v_cvt_pk_bf16_f32 v25, v102, v103
	v_cvt_pk_bf16_f32 v26, v104, v105
	v_cvt_pk_bf16_f32 v27, v106, v107
	v_cvt_pk_bf16_f32 v28, v108, v109
	v_cvt_pk_bf16_f32 v29, v110, v111
	v_cvt_pk_bf16_f32 v30, v112, v113
	v_cvt_pk_bf16_f32 v31, v114, v115
	v_cvt_pk_bf16_f32 v32, v116, v117
	v_cvt_pk_bf16_f32 v33, v118, v119
	v_cvt_pk_bf16_f32 v34, v120, v121
	v_cvt_pk_bf16_f32 v35, v122, v123
	v_cvt_pk_bf16_f32 v36, v124, v125
	v_cvt_pk_bf16_f32 v37, v126, v127
	v_cvt_pk_bf16_f32 v38, v128, v129
	v_cvt_pk_bf16_f32 v39, v130, v131
	s_nop 0
	ds_write_b128 v13, v[24:27]
	ds_write_b128 v13, v[28:31] offset:16
	ds_write_b128 v13, v[32:35] offset:32
	ds_write_b128 v13, v[36:39] offset:48
	s_add_i32 s39, s39, s100
	s_cmp_ge_i32 s39, s101
	s_cbranch_scc1 .Lp2_g_nonext
; #define LAS __attribute__((address_space(3)))
; DI unsigned pk2(float a, float b) { f32x2 f = {a, b}; bf16v2 r = __builtin_convertvector(f, bf16v2); return __builtin_bit_cast(unsigned, r); }
; DI void phase2(CP& p, LAS unsigned char* lds, int wid) {
;     ...
;             { const int t = tid >> 2, sq = (tid & 3) * 32; const float* wrow = p.w_s + ((size_t)h * 128 + t) * 128 + sq;
; #pragma unroll
;               for (int e = 0; e < 4; ++e) { const f32x4 a = *(const f32x4*)(wrow + e * 8), b = *(const f32x4*)(wrow + e * 8 + 4); const int s0 = sq + e * 8;
;                   const float mk = ((s0 >> 6) <= (t >> 6)) ? 1.f : 0.f;
;                   u32x4 w; w.x = pk2(a[0] * mk * rsl[s0], a[1] * mk * rsl[s0 + 1]); w.y = pk2(a[2] * mk * rsl[s0 + 2], a[3] * mk * rsl[s0 + 3]);
;                   w.z = pk2(b[0] * mk * rsl[s0 + 4], b[1] * mk * rsl[s0 + 5]); w.w = pk2(b[2] * mk * rsl[s0 + 6], b[3] * mk * rsl[s0 + 7]);
;                   *(LAS u32x4*)(wm + t * 272 + s0 * 2) = w; } }
;             __syncthreads();
;             const int ch = h * 128 + 16 * wid + fr; const bf16_t* vt = WSB(OFF_VT) + (size_t)ch * 8192 + t0 + 8 * fq;
;             bf16x8 bfr[4];
; #pragma unroll
;             for (int ks = 0; ks < 4; ++ks) bfr[ks] = *(const bf16x8*)(vt + 32 * ks);
;             f32x4 acc[8];
; #pragma unroll
;             for (int tt = 0; tt < 8; ++tt) { acc[tt] = (f32x4){0.f, 0.f, 0.f, 0.f};
; #pragma unroll
;                 for (int ks = 0; ks < 4; ++ks) { const bf16x8 af = *(const LAS bf16x8*)(wm + (16 * tt + fr) * 272 + (32 * ks + 8 * fq) * 2);
;                     acc[tt] = __builtin_amdgcn_mfma_f32_16x16x32_bf16(bfr[ks], af, acc[tt], 0, 0, 0); } }
	s_add_i32 s2, s39, 0xffffff00
	s_and_b32 s3, s2, 7
	s_lshr_b32 s2, s2, 3
	s_lshl_b32 s2, s2, 7
	s_lshl_b32 s4, s2, 2
	s_add_u32 s10, s20, s4
	s_addc_u32 s11, s21, 0
	global_load_dword v22, v20, s[10:11]
	s_lshl_b32 s4, s3, 16
	s_add_u32 s10, s14, s4
	s_addc_u32 s11, s15, 0
	global_load_dwordx4 v[100:103], v8, s[10:11]
	global_load_dwordx4 v[104:107], v8, s[10:11] offset:16
	global_load_dwordx4 v[108:111], v8, s[10:11] offset:32
	global_load_dwordx4 v[112:115], v8, s[10:11] offset:48
	global_load_dwordx4 v[116:119], v8, s[10:11] offset:64
	global_load_dwordx4 v[120:123], v8, s[10:11] offset:80
	global_load_dwordx4 v[124:127], v8, s[10:11] offset:96
	global_load_dwordx4 v[128:131], v8, s[10:11] offset:112
	s_lshl_b32 s4, s3, 21
	s_lshl_b32 s5, s2, 1
	s_add_i32 s4, s4, s5
	s_add_u32 s10, s28, s4
	s_addc_u32 s11, s29, 0
	global_load_dwordx4 v[132:135], v14, s[10:11]
	global_load_dwordx4 v[136:139], v14, s[10:11] offset:64
	global_load_dwordx4 v[140:143], v14, s[10:11] offset:128
	global_load_dwordx4 v[144:147], v14, s[10:11] offset:192
	s_lshl_b32 s4, s3, 9
	s_add_u32 s10, s12, s4
	s_addc_u32 s11, s13, 0
	global_load_dwordx4 v[148:151], v15, s[10:11]
	s_add_u32 s10, s22, s4
	s_addc_u32 s11, s23, 0
	global_load_dword v176, v16, s[10:11]
	global_load_dword v178, v16, s[10:11] offset:64
	global_load_dword v180, v16, s[10:11] offset:128
	global_load_dword v182, v16, s[10:11] offset:192
	global_load_dword v184, v16, s[10:11] offset:256
	global_load_dword v186, v16, s[10:11] offset:320
	global_load_dword v188, v16, s[10:11] offset:384
	global_load_dword v190, v16, s[10:11] offset:448
	s_lshl_b32 s4, s2, 11
	s_lshl_b32 s5, s3, 8
	s_add_i32 s4, s4, s5
	s_add_u32 s10, s30, s4
	s_addc_u32 s11, s31, 0
	global_load_dwordx2 v[160:161], v17, s[10:11]
	s_add_u32 s10, s10, 0x8000
	s_addc_u32 s11, s11, 0
	global_load_dwordx2 v[162:163], v17, s[10:11]
	s_add_u32 s10, s10, 0x8000
	s_addc_u32 s11, s11, 0
	global_load_dwordx2 v[164:165], v17, s[10:11]
	s_add_u32 s10, s10, 0x8000
	s_addc_u32 s11, s11, 0
	global_load_dwordx2 v[166:167], v17, s[10:11]
	s_add_u32 s10, s10, 0x8000
	s_addc_u32 s11, s11, 0
	global_load_dwordx2 v[168:169], v17, s[10:11]
	s_add_u32 s10, s10, 0x8000
	s_addc_u32 s11, s11, 0
	global_load_dwordx2 v[170:171], v17, s[10:11]
	s_add_u32 s10, s10, 0x8000
	s_addc_u32 s11, s11, 0
	global_load_dwordx2 v[172:173], v17, s[10:11]
	s_add_u32 s10, s10, 0x8000
	s_addc_u32 s11, s11, 0
	global_load_dwordx2 v[174:175], v17, s[10:11]
	s_lshl_b32 s4, s2, 12
	s_add_i32 s4, s4, s5
	s_add_u32 s8, s36, s4
	s_addc_u32 s9, s37, 0
.Lp2_g_nonext:
	s_waitcnt lgkmcnt(0)
	s_barrier
	ds_read_b128 v[24:27], v19 offset:0
	ds_read_b128 v[28:31], v19 offset:64
	ds_read_b128 v[32:35], v19 offset:128
	ds_read_b128 v[36:39], v19 offset:192
	ds_read_b128 v[40:43], v19 offset:4352
	ds_read_b128 v[44:47], v19 offset:4416
	ds_read_b128 v[48:51], v19 offset:4480
	ds_read_b128 v[52:55], v19 offset:4544
	s_waitcnt lgkmcnt(7)
	v_mfma_f32_16x16x32_bf16 v[56:59], v[192:195], v[24:27], 0
	s_waitcnt lgkmcnt(6)
	v_mfma_f32_16x16x32_bf16 v[56:59], v[196:199], v[28:31], v[56:59]
	s_waitcnt lgkmcnt(5)
	v_mfma_f32_16x16x32_bf16 v[56:59], v[200:203], v[32:35], v[56:59]
	s_waitcnt lgkmcnt(4)
	v_mfma_f32_16x16x32_bf16 v[56:59], v[204:207], v[36:39], v[56:59]
	ds_read_b128 v[24:27], v19 offset:8704
	ds_read_b128 v[28:31], v19 offset:8768
	ds_read_b128 v[32:35], v19 offset:8832
	ds_read_b128 v[36:39], v19 offset:8896
	s_waitcnt lgkmcnt(7)
	v_mfma_f32_16x16x32_bf16 v[60:63], v[192:195], v[40:43], 0
	s_waitcnt lgkmcnt(6)
	v_mfma_f32_16x16x32_bf16 v[60:63], v[196:199], v[44:47], v[60:63]
	s_waitcnt lgkmcnt(5)
	v_mfma_f32_16x16x32_bf16 v[60:63], v[200:203], v[48:51], v[60:63]
	s_waitcnt lgkmcnt(4)
	v_mfma_f32_16x16x32_bf16 v[60:63], v[204:207], v[52:55], v[60:63]
	ds_read_b128 v[40:43], v19 offset:13056
	ds_read_b128 v[44:47], v19 offset:13120
	ds_read_b128 v[48:51], v19 offset:13184
	ds_read_b128 v[52:55], v19 offset:13248
	s_waitcnt lgkmcnt(7)
	v_mfma_f32_16x16x32_bf16 v[64:67], v[192:195], v[24:27], 0
	s_waitcnt lgkmcnt(6)
	v_mfma_f32_16x16x32_bf16 v[64:67], v[196:199], v[28:31], v[64:67]
	s_waitcnt lgkmcnt(5)
	v_mfma_f32_16x16x32_bf16 v[64:67], v[200:203], v[32:35], v[64:67]
	s_waitcnt lgkmcnt(4)
	v_mfma_f32_16x16x32_bf16 v[64:67], v[204:207], v[36:39], v[64:67]
	ds_read_b128 v[24:27], v19 offset:17408
	ds_read_b128 v[28:31], v19 offset:17472
	ds_read_b128 v[32:35], v19 offset:17536
	ds_read_b128 v[36:39], v19 offset:17600
	s_waitcnt lgkmcnt(7)
	v_mfma_f32_16x16x32_bf16 v[68:71], v[192:195], v[40:43], 0
	s_waitcnt lgkmcnt(6)
	v_mfma_f32_16x16x32_bf16 v[68:71], v[196:199], v[44:47], v[68:71]
	s_waitcnt lgkmcnt(5)
	v_mfma_f32_16x16x32_bf16 v[68:71], v[200:203], v[48:51], v[68:71]
	s_waitcnt lgkmcnt(4)
	v_mfma_f32_16x16x32_bf16 v[68:71], v[204:207], v[52:55], v[68:71]
	ds_read_b128 v[40:43], v19 offset:21760
	ds_read_b128 v[44:47], v19 offset:21824
	ds_read_b128 v[48:51], v19 offset:21888
	ds_read_b128 v[52:55], v19 offset:21952
	s_waitcnt lgkmcnt(7)
	v_mfma_f32_16x16x32_bf16 v[72:75], v[192:195], v[24:27], 0
	s_waitcnt lgkmcnt(6)
	v_mfma_f32_16x16x32_bf16 v[72:75], v[196:199], v[28:31], v[72:75]
	s_waitcnt lgkmcnt(5)
	v_mfma_f32_16x16x32_bf16 v[72:75], v[200:203], v[32:35], v[72:75]
	s_waitcnt lgkmcnt(4)
	v_mfma_f32_16x16x32_bf16 v[72:75], v[204:207], v[36:39], v[72:75]
	ds_read_b128 v[24:27], v19 offset:26112
	ds_read_b128 v[28:31], v19 offset:26176
	ds_read_b128 v[32:35], v19 offset:26240
	ds_read_b128 v[36:39], v19 offset:26304
	s_waitcnt lgkmcnt(7)
	v_mfma_f32_16x16x32_bf16 v[76:79], v[192:195], v[40:43], 0
	s_waitcnt lgkmcnt(6)
; DI u32x2 pk4(f32x4 v) { u32x2 r; r.x = pk2(v[0], v[1]); r.y = pk2(v[2], v[3]); return r; }
; DI float bf_lo(unsigned w) { return __uint_as_float(w << 16); }
; DI float bf_hi(unsigned w) { return __uint_as_float(w & 0xffff0000u); }
; DI void phase2(CP& p, LAS unsigned char* lds, int wid) {
;     ...
;             const int d0 = h * 128 + 16 * wid + 4 * fq; const f32x4 gv = *(const f32x4*)(p.g_v + d0);
; #pragma unroll
;             for (int tt = 0; tt < 8; ++tt) { const int t = 16 * tt + fr, tok = t0 + t; const float bs = p.b_s[h * 128 + t];
;                 const u32x2 uw = *(const u32x2*)(WSB(OFF_U) + (size_t)tok * 1024 + d0);
;                 f32x4 a; a[0] = bf_lo(uw.x) * (acc[tt][0] * gv[0] + bs); a[1] = bf_hi(uw.x) * (acc[tt][1] * gv[1] + bs);
;                 a[2] = bf_lo(uw.y) * (acc[tt][2] * gv[2] + bs); a[3] = bf_hi(uw.y) * (acc[tt][3] * gv[3] + bs);
;                 *(u32x2*)(WSB(OFF_CAT) + (size_t)tok * 2048 + d0) = pk4(a); }
;             __syncthreads();
	v_mfma_f32_16x16x32_bf16 v[76:79], v[196:199], v[44:47], v[76:79]
	s_waitcnt lgkmcnt(5)
	v_mfma_f32_16x16x32_bf16 v[76:79], v[200:203], v[48:51], v[76:79]
	s_waitcnt lgkmcnt(4)
	v_mfma_f32_16x16x32_bf16 v[76:79], v[204:207], v[52:55], v[76:79]
	ds_read_b128 v[40:43], v19 offset:30464
	ds_read_b128 v[44:47], v19 offset:30528
	ds_read_b128 v[48:51], v19 offset:30592
	ds_read_b128 v[52:55], v19 offset:30656
	s_waitcnt lgkmcnt(7)
	v_mfma_f32_16x16x32_bf16 v[80:83], v[192:195], v[24:27], 0
	s_waitcnt lgkmcnt(6)
	v_mfma_f32_16x16x32_bf16 v[80:83], v[196:199], v[28:31], v[80:83]
	s_waitcnt lgkmcnt(5)
	v_mfma_f32_16x16x32_bf16 v[80:83], v[200:203], v[32:35], v[80:83]
	s_waitcnt lgkmcnt(4)
	v_mfma_f32_16x16x32_bf16 v[80:83], v[204:207], v[36:39], v[80:83]
	s_waitcnt lgkmcnt(3)
	v_mfma_f32_16x16x32_bf16 v[84:87], v[192:195], v[40:43], 0
	s_waitcnt lgkmcnt(2)
	v_mfma_f32_16x16x32_bf16 v[84:87], v[196:199], v[44:47], v[84:87]
	s_waitcnt lgkmcnt(1)
	v_mfma_f32_16x16x32_bf16 v[84:87], v[200:203], v[48:51], v[84:87]
	s_waitcnt lgkmcnt(0)
	v_mfma_f32_16x16x32_bf16 v[84:87], v[204:207], v[52:55], v[84:87]
	s_nop 7
	v_pk_fma_f32 v[56:57], v[56:57], v[208:209], v[228:229] op_sel_hi:[1,1,0]
	v_pk_fma_f32 v[58:59], v[58:59], v[210:211], v[228:229] op_sel_hi:[1,1,0]
	v_lshlrev_b32_e32 v24, 16, v212
	v_and_b32_e32 v25, 0xffff0000, v212
	v_lshlrev_b32_e32 v26, 16, v213
	v_and_b32_e32 v27, 0xffff0000, v213
	v_pk_mul_f32 v[56:57], v[56:57], v[24:25]
	v_pk_mul_f32 v[58:59], v[58:59], v[26:27]
	v_cvt_pk_bf16_f32 v56, v56, v57
	v_cvt_pk_bf16_f32 v57, v58, v59
	global_store_dwordx2 v18, v[56:57], s[18:19]
	v_pk_fma_f32 v[60:61], v[60:61], v[208:209], v[230:231] op_sel_hi:[1,1,0]
	v_pk_fma_f32 v[62:63], v[62:63], v[210:211], v[230:231] op_sel_hi:[1,1,0]
	v_lshlrev_b32_e32 v24, 16, v214
	v_and_b32_e32 v25, 0xffff0000, v214
	v_lshlrev_b32_e32 v26, 16, v215
	v_and_b32_e32 v27, 0xffff0000, v215
	v_pk_mul_f32 v[60:61], v[60:61], v[24:25]
	v_pk_mul_f32 v[62:63], v[62:63], v[26:27]
	v_cvt_pk_bf16_f32 v60, v60, v61
	v_cvt_pk_bf16_f32 v61, v62, v63
	s_add_u32 s18, s18, 0x10000
	s_addc_u32 s19, s19, 0
	global_store_dwordx2 v18, v[60:61], s[18:19]
	v_pk_fma_f32 v[64:65], v[64:65], v[208:209], v[232:233] op_sel_hi:[1,1,0]
	v_pk_fma_f32 v[66:67], v[66:67], v[210:211], v[232:233] op_sel_hi:[1,1,0]
	v_lshlrev_b32_e32 v24, 16, v216
	v_and_b32_e32 v25, 0xffff0000, v216
	v_lshlrev_b32_e32 v26, 16, v217
	v_and_b32_e32 v27, 0xffff0000, v217
	v_pk_mul_f32 v[64:65], v[64:65], v[24:25]
	v_pk_mul_f32 v[66:67], v[66:67], v[26:27]
	v_cvt_pk_bf16_f32 v64, v64, v65
	v_cvt_pk_bf16_f32 v65, v66, v67
	s_add_u32 s18, s18, 0x10000
	s_addc_u32 s19, s19, 0
	global_store_dwordx2 v18, v[64:65], s[18:19]
	v_pk_fma_f32 v[68:69], v[68:69], v[208:209], v[234:235] op_sel_hi:[1,1,0]
	v_pk_fma_f32 v[70:71], v[70:71], v[210:211], v[234:235] op_sel_hi:[1,1,0]
	v_lshlrev_b32_e32 v24, 16, v218
	v_and_b32_e32 v25, 0xffff0000, v218
	v_lshlrev_b32_e32 v26, 16, v219
	v_and_b32_e32 v27, 0xffff0000, v219
	v_pk_mul_f32 v[68:69], v[68:69], v[24:25]
	v_pk_mul_f32 v[70:71], v[70:71], v[26:27]
	v_cvt_pk_bf16_f32 v68, v68, v69
	v_cvt_pk_bf16_f32 v69, v70, v71
	s_add_u32 s18, s18, 0x10000
	s_addc_u32 s19, s19, 0
	global_store_dwordx2 v18, v[68:69], s[18:19]
	v_pk_fma_f32 v[72:73], v[72:73], v[208:209], v[236:237] op_sel_hi:[1,1,0]
	v_pk_fma_f32 v[74:75], v[74:75], v[210:211], v[236:237] op_sel_hi:[1,1,0]
	v_lshlrev_b32_e32 v24, 16, v220
	v_and_b32_e32 v25, 0xffff0000, v220
	v_lshlrev_b32_e32 v26, 16, v221
	v_and_b32_e32 v27, 0xffff0000, v221
	v_pk_mul_f32 v[72:73], v[72:73], v[24:25]
	v_pk_mul_f32 v[74:75], v[74:75], v[26:27]
	v_cvt_pk_bf16_f32 v72, v72, v73
	v_cvt_pk_bf16_f32 v73, v74, v75
	s_add_u32 s18, s18, 0x10000
	s_addc_u32 s19, s19, 0
	global_store_dwordx2 v18, v[72:73], s[18:19]
	v_pk_fma_f32 v[76:77], v[76:77], v[208:209], v[238:239] op_sel_hi:[1,1,0]
	v_pk_fma_f32 v[78:79], v[78:79], v[210:211], v[238:239] op_sel_hi:[1,1,0]
	v_lshlrev_b32_e32 v24, 16, v222
	v_and_b32_e32 v25, 0xffff0000, v222
	v_lshlrev_b32_e32 v26, 16, v223
	v_and_b32_e32 v27, 0xffff0000, v223
	v_pk_mul_f32 v[76:77], v[76:77], v[24:25]
	v_pk_mul_f32 v[78:79], v[78:79], v[26:27]
	v_cvt_pk_bf16_f32 v76, v76, v77
	v_cvt_pk_bf16_f32 v77, v78, v79
	s_add_u32 s18, s18, 0x10000
	s_addc_u32 s19, s19, 0
	global_store_dwordx2 v18, v[76:77], s[18:19]
	v_pk_fma_f32 v[80:81], v[80:81], v[208:209], v[240:241] op_sel_hi:[1,1,0]
	v_pk_fma_f32 v[82:83], v[82:83], v[210:211], v[240:241] op_sel_hi:[1,1,0]
	v_lshlrev_b32_e32 v24, 16, v224
	v_and_b32_e32 v25, 0xffff0000, v224
	v_lshlrev_b32_e32 v26, 16, v225
	v_and_b32_e32 v27, 0xffff0000, v225
	v_pk_mul_f32 v[80:81], v[80:81], v[24:25]
	v_pk_mul_f32 v[82:83], v[82:83], v[26:27]
	v_cvt_pk_bf16_f32 v80, v80, v81
	v_cvt_pk_bf16_f32 v81, v82, v83
	s_add_u32 s18, s18, 0x10000
	s_addc_u32 s19, s19, 0
	global_store_dwordx2 v18, v[80:81], s[18:19]
	v_pk_fma_f32 v[84:85], v[84:85], v[208:209], v[242:243] op_sel_hi:[1,1,0]
	v_pk_fma_f32 v[86:87], v[86:87], v[210:211], v[242:243] op_sel_hi:[1,1,0]
	v_lshlrev_b32_e32 v24, 16, v226
	v_and_b32_e32 v25, 0xffff0000, v226
	v_lshlrev_b32_e32 v26, 16, v227
	v_and_b32_e32 v27, 0xffff0000, v227
	v_pk_mul_f32 v[84:85], v[84:85], v[24:25]
	v_pk_mul_f32 v[86:87], v[86:87], v[26:27]
	v_cvt_pk_bf16_f32 v84, v84, v85
	v_cvt_pk_bf16_f32 v85, v86, v87
	s_add_u32 s18, s18, 0x10000
	s_addc_u32 s19, s19, 0
	global_store_dwordx2 v18, v[84:85], s[18:19]
	s_cmp_lt_i32 s39, s101
	s_cbranch_scc1 .Lp2_g_item
	s_branch .Lp2_done
.Lp2_next:
	s_add_i32 s39, s39, s100
	s_cmp_lt_i32 s39, s101
	s_cbranch_scc1 .Lp2_item
.Lp2_done:
	s_cmp_lg_u32 s98, 0
	s_cbranch_scc1 .Lp2_ret

; DI u32x2 pk4(f32x4 v) { u32x2 r; r.x = pk2(v[0], v[1]); r.y = pk2(v[2], v[3]); return r; }
; DI void phase2(CP& p, LAS unsigned char* lds, int wid) {
;     ...
;     for (int it = blockIdx.x; it < 256 + 512; it += gridDim.x) {
;         if (it < 256) {
;             const int gt = it * NTHR + tid, c = (gt & 255) * 4, run = gt >> 8, g = c >> 8, win = 2 << g;
;             const int t0 = run * 16, tb = t0 & (SEQ - 1);
;             f32x4 sum = {0.f, 0.f, 0.f, 0.f};
;             for (int j = 1; j < win; ++j) if (tb - j >= 0) sum += *(const f32x4*)(Z + (size_t)(t0 - j) * 1024 + c);
;             for (int i = 0; i < 16; ++i) { const int t = t0 + i, pos = tb + i; const f32x4 zc = *(const f32x4*)(Z + (size_t)t * 1024 + c);
;                 sum += zc; const float cnt = (float)((pos + 1) < win ? (pos + 1) : win); const f32x4 d = sum / cnt - zc;
;                 *(u32x2*)(DP + (size_t)t * 1024 + c) = pk4(d);
;                 if (pos - win + 1 >= 0) sum -= *(const f32x4*)(Z + (size_t)(t - win + 1) * 1024 + c); }
;         } else {
;             const int item = it - 256, nb = item >> 3, h = item & 7, t0 = nb * 128;
.LBB0_546:
	s_and_b64 vcc, exec, s[4:5]
	s_cbranch_vccz .Lp2_skip
	s_cmpk_eq_i32 s7, 0x100
	s_cbranch_scc0 .Lp2_skip
	s_and_b32 s12, s6, 31
	s_lshl_b32 s12, s12, 3
	s_lshr_b32 s13, s6, 5
	s_or_b32 s12, s12, s13
	s_add_i32 s99, s12, 0x100
	s_add_i32 s101, s99, 1
	s_cmpk_lt_u32 s12, 128
	s_cbranch_scc1 .Lp2_call
	s_addk_i32 s12, -128
	s_mul_i32 s12, s12, 3
	s_add_i32 s99, s12, 0x180
	s_add_i32 s101, s99, 3
.Lp2_call:
	s_mov_b32 s100, 1
	s_mov_b32 s98, 8
	s_mov_b64 s[4:5], s[0:1]
	v_mbcnt_hi_u32_b32 v2, -1, v254
	s_branch .Lp2_entry
